# fused out-projection epilogue: row-panel exchange via tagged 8-byte slots (partial sum + phase tag in one store; readers poll the slots) - no store-completion wait, no counter round trip, one barrier
# speedup vs baseline: 1.0050x; 1.0050x over previous
; __device__ __forceinline__ unsigned pk2(float lo, float hi) { unsigned r; asm volatile("v_cvt_pk_bf16_f32 %0, %1, %2" : "=v"(r) : "v"(lo), "v"(hi)); return r; }
; __device__ __forceinline__ void phase_prep(const Args& a, float* ldsf) {
;     ...
;     {
;         const int gt = blockIdx.x * NTHREADS + tid, NGT = gridDim.x * NTHREADS;
;         const int per = (SSD_IN_PAD - SSD_IN_N) * 1024 * 2 / 16;
;         for (int i = gt; i < 2 * per; i += NGT) { const int j = i / per, r = i % per; ((uint4*)(ws + WS_SSDIN + j * SZ_SSDIN1 + (size_t)SSD_IN_N * 1024 * 2))[r] = make_uint4(0, 0, 0, 0); }
;         for (int i = gt; i < 2 * M_; i += NGT) ((unsigned long long*)(ws + WS_SSQY))[i] = 0ull;
;     }
;     const float* x = a.in[0]; bf16_t* XB = (bf16_t*)(ws + WS_XB); float* RSX = (float*)(ws + WS_RSX);
;     for (int row = gw; row < M_; row += NGW) {
;         float s2 = 0.f;
; #pragma unroll
;         for (int jj = 0; jj < 4; ++jj) {
;             const size_t idx = (size_t)row * 1024 + 256 * jj + 4 * lane;
;             const f32x4 v = *(const f32x4*)(x + idx);
;             u32x2 w; w.x = pk2(v[0], v[1]); w.y = pk2(v[2], v[3]); *(u32x2*)(XB + idx) = w;
;             s2 += (v[0] * v[0] + v[1] * v[1]) + (v[2] * v[2] + v[3] * v[3]);
;         }
;         s2 = wave_sum(s2);
;         if (lane == 0) *(f32x4*)(RSX + (size_t)row * 4) = (f32x4){s2, 0.f, 0.f, 0.f};
;     }
.LBB0_548:
	s_or_b64 exec, exec, s[0:1]
	v_ashrrev_i32_e32 v1, 6, v13
	v_readlane_b32 s0, v253, 58
	s_nop 1
	v_add_u32_e32 v10, s0, v1
	s_movk_i32 s0, 0x4000
	v_cmp_gt_i32_e32 vcc, s0, v10
	s_and_saveexec_b64 s[4:5], vcc
	s_cbranch_execz .LBB0_7
	v_readlane_b32 s8, v253, 20
	v_readlane_b32 s9, v253, 21
	v_and_b32_e32 v34, 63, v13
	v_lshl_or_b32 v34, v10, 6, v34
	v_lshlrev_b32_e32 v34, 2, v34
	v_mov_b32_e32 v35, 0
	s_nop 1
	global_store_dword v34, v35, s[8:9]
	v_ashrrev_i32_e32 v11, 31, v10
	v_mov_b64_e32 v[4:5], 0x15d40000
	v_and_b32_e32 v1, 63, v13
	v_lshl_add_u64 v[12:13], v[10:11], 4, v[4:5]
	v_lshlrev_b64 v[4:5], 12, v[10:11]
	v_readlane_b32 s2, v254, 47
	v_lshlrev_b64 v[14:15], 11, v[10:11]
	v_lshl_or_b32 v4, v1, 4, v4
	v_readlane_b32 s3, v254, 48
	v_cmp_eq_u32_e64 s[0:1], 0, v1
	v_lshl_or_b32 v14, v1, 3, v14
	v_lshl_add_u64 v[16:17], s[2:3], 0, v[4:5]
	s_mov_b64 s[6:7], 0
	s_branch .LBB0_551

; #define LAS __attribute__((address_space(3)))
;     __device__ __forceinline__ void fused(f32x4 (&acc)[2][2][4][2], const pg8::Unit& u, int wr, int wc, int fr, int fq, LAS unsigned char* lds, int wid, int lane) const {
;     ...
;         asm volatile("s_waitcnt lgkmcnt(0)" ::: "memory"); __builtin_amdgcn_s_barrier(); asm volatile("" ::: "memory");
;         if (tid < 256) {
;             const f32x4 p = *(const LAS f32x4*)(P + tid * 4);
;             __hip_atomic_store(xch + ((size_t)u.pm * 4 + u.pn) * 256 + tid, (p[0] + p[1]) + (p[2] + p[3]), __ATOMIC_RELAXED, __HIP_MEMORY_SCOPE_AGENT);
.LBB0_591:
	s_or_b64 exec, exec, s[0:1]
	s_waitcnt lgkmcnt(0)
	s_barrier
	s_movk_i32 s0, 0x100
	v_cmp_gt_i32_e64 s[6:7], s0, v4
	v_ashrrev_i32_e32 v5, 31, v4
	v_lshl_add_u32 v225, v4, 4, 0
	s_and_b64 s[0:1], s[22:23], exec
	s_cselect_b32 s0, 16, 0
	s_lshl_b32 s11, s24, 5
	s_or_b32 s11, s11, s0
	s_add_i32 s11, s11, 16
	s_or_b32 s11, s11, 0x5a5a0000
	s_and_saveexec_b64 s[0:1], s[6:7]
	s_cbranch_execz .LBB0_593
	s_waitcnt lgkmcnt(0)
	ds_read_b128 v[10:13], v225
	s_ashr_i32 s75, s74, 31
	s_ashr_i32 s69, s68, 31
	s_lshl_b64 s[2:3], s[74:75], 13
	v_readlane_b32 s8, v253, 20
	s_add_u32 s8, s8, s2
	v_readlane_b32 s2, v253, 21
	s_addc_u32 s9, s2, s3
	s_lshl_b64 s[2:3], s[68:69], 11
	s_add_u32 s2, s8, s2
	s_waitcnt lgkmcnt(0)
	v_mov_b32_e32 v16, v11
	v_mov_b32_e32 v17, v12
	v_mov_b32_e32 v11, v13
	s_addc_u32 s3, s9, s3
	v_pk_add_f32 v[10:11], v[16:17], v[10:11]
	v_lshl_add_u64 v[14:15], v[4:5], 3, s[2:3]
	v_pk_add_f32 v[10:11], v[10:11], v[10:11] op_sel:[0,1] op_sel_hi:[1,0]
	s_nop 0
	v_mov_b32_e32 v11, s11
	global_store_dwordx2 v[14:15], v[10:11], off sc1

;     __device__ __forceinline__ void fused(f32x4 (&acc)[2][2][4][2], const pg8::Unit& u, int wr, int wc, int fr, int fq, LAS unsigned char* lds, int wid, int lane) const {
;     ...
;         asm volatile("s_waitcnt vmcnt(0)" ::: "memory");
;         if (wid < 4 && lane == 0) __hip_atomic_fetch_add(cnt + 64 * u.pm, 1u, __ATOMIC_RELAXED, __HIP_MEMORY_SCOPE_AGENT);
;         const int cb = u.pn * 256 + wc * 32 + 8 * fq;
;         uint4 xold[4][2];
; #pragma unroll
;         for (int m = 0; m < 4; ++m)
; #pragma unroll
;             for (int bj = 0; bj < 2; ++bj) xold[m][bj] = *(const uint4*)(XB + (size_t)(u.pm * 256 + wr * 64 + m * 16 + fr) * 1024 + cb + bj * 128);
;         if (wid == 0) {
;             unsigned sp = 0;
;             while ((unsigned)__builtin_amdgcn_readfirstlane(__hip_atomic_load(cnt + 64 * u.pm, __ATOMIC_RELAXED, __HIP_MEMORY_SCOPE_AGENT)) < target) { __builtin_amdgcn_s_sleep(1); if (++sp > (1u << 22)) break; }
;         }
;         asm volatile("s_waitcnt lgkmcnt(0)" ::: "memory"); __builtin_amdgcn_s_barrier(); asm volatile("" ::: "memory");
;         if (tid < 256) {
;             float t = 0.f;
; #pragma unroll
;             for (int k = 0; k < 4; ++k) t += __hip_atomic_load(xch + ((size_t)u.pm * 4 + k) * 256 + tid, __ATOMIC_RELAXED, __HIP_MEMORY_SCOPE_AGENT);
;             S[tid] = rsqrtf(t * (1.0f / 1024.f) + EPS_);
;         }
.LBB0_596:
	s_lshl_b32 s0, s36, 5
	s_lshl_b32 s1, s68, 8
	s_waitcnt lgkmcnt(0)
	v_lshrrev_b32_e32 v10, 1, v220
	s_or_b32 s0, s1, s0
	v_and_or_b32 v102, v10, 24, s0
	s_lshl_b32 s2, s74, 8
	v_readlane_b32 s0, v255, 38
	v_readlane_b32 s1, v255, 39
	s_add_i32 s3, s2, s0
	v_or_b32_e32 v10, s3, v175
	v_readlane_b32 s0, v253, 14
	v_ashrrev_i32_e32 v103, 31, v102
	v_readlane_b32 s1, v253, 15
	v_ashrrev_i32_e32 v11, 31, v10
	v_lshlrev_b64 v[12:13], 11, v[10:11]
	v_lshl_add_u64 v[98:99], v[102:103], 1, s[0:1]
	v_lshl_add_u64 v[12:13], v[98:99], 0, v[12:13]
	global_load_dwordx4 v[54:57], v[12:13], off
	global_load_dwordx4 v[50:53], v[12:13], off offset:256
	v_or_b32_e32 v12, 16, v10
	v_ashrrev_i32_e32 v13, 31, v12
	v_lshlrev_b64 v[12:13], 11, v[12:13]
	v_lshl_add_u64 v[12:13], v[98:99], 0, v[12:13]
	global_load_dwordx4 v[46:49], v[12:13], off
	global_load_dwordx4 v[42:45], v[12:13], off offset:256
	v_or_b32_e32 v12, 32, v10
	v_or_b32_e32 v10, 48, v10
	v_ashrrev_i32_e32 v13, 31, v12
	v_ashrrev_i32_e32 v11, 31, v10
	v_lshlrev_b64 v[12:13], 11, v[12:13]
	v_lshlrev_b64 v[10:11], 11, v[10:11]
	v_lshl_add_u64 v[12:13], v[98:99], 0, v[12:13]
	v_lshl_add_u64 v[10:11], v[98:99], 0, v[10:11]
	global_load_dwordx4 v[38:41], v[12:13], off
	global_load_dwordx4 v[34:37], v[12:13], off offset:256
	global_load_dwordx4 v[30:33], v[10:11], off
	global_load_dwordx4 v[26:29], v[10:11], off offset:256
	s_and_saveexec_b64 s[0:1], s[6:7]
	s_cbranch_execz .LBB0_607
	s_ashr_i32 s75, s74, 31
	s_lshl_b64 s[8:9], s[74:75], 13
	v_readlane_b32 s10, v253, 20
	s_add_u32 s8, s10, s8
	v_readlane_b32 s10, v253, 21
	s_addc_u32 s9, s10, s9
	v_lshl_add_u64 v[10:11], v[4:5], 3, s[8:9]
	s_mov_b64 s[8:9], 0x1000
	v_lshl_add_u64 v[12:13], v[10:11], 0, s[8:9]
	s_movk_i32 s10, 0x1000
.Lxc_spin:
	global_load_dwordx2 v[14:15], v[10:11], off sc1
	global_load_dwordx2 v[16:17], v[10:11], off offset:2048 sc1
	global_load_dwordx2 v[18:19], v[12:13], off sc1
	global_load_dwordx2 v[20:21], v[12:13], off offset:2048 sc1
	s_waitcnt vmcnt(0)
	v_cmp_eq_u32_e32 vcc, s11, v15
	v_cmp_eq_u32_e64 s[82:83], s11, v17
	s_and_b64 vcc, vcc, s[82:83]
	v_cmp_eq_u32_e64 s[82:83], s11, v19
	s_and_b64 vcc, vcc, s[82:83]
	v_cmp_eq_u32_e64 s[82:83], s11, v21
	s_and_b64 vcc, vcc, s[82:83]
	s_xor_b64 s[82:83], vcc, exec
	s_cmp_eq_u64 s[82:83], 0
	s_cbranch_scc1 .Lxc_ready
	s_add_i32 s10, s10, -1
	s_cmp_eq_u32 s10, 0
	s_cbranch_scc1 .Lxc_ready
	s_sleep 1
	s_branch .Lxc_spin
.Lxc_ready:
	s_mov_b32 s8, 0x800000
	v_add_f32_e32 v5, 0, v14
	v_add_f32_e32 v5, v5, v16
	v_add_f32_e32 v5, v5, v18
	v_add_f32_e32 v5, v5, v20
	v_fmamk_f32 v5, v5, 0x3a800000, v170
	v_cmp_gt_f32_e32 vcc, s8, v5
	v_mul_f32_e32 v10, 0x4b800000, v5
	s_nop 0
	v_cndmask_b32_e32 v5, v5, v10, vcc
	v_rsq_f32_e32 v5, v5
	s_nop 0
	v_mul_f32_e32 v10, 0x45800000, v5
	v_cndmask_b32_e32 v5, v5, v10, vcc
	v_lshl_add_u32 v10, v4, 2, 0
	ds_write_b32 v10, v5 offset:4096
